# v22 plus GEMM1 next-tile prefetch, GEMM3 tile-type alternation per round, no ack wait after barrier release adds
# speedup vs baseline: 1.0059x; 1.0055x over previous
.LBB0_120:
	s_or_b64 exec, exec, s[8:9]
	s_mov_b64 s[8:9], exec
	v_mbcnt_lo_u32_b32 v2, s8, 0
	v_mbcnt_hi_u32_b32 v2, s9, v2
	v_cmp_eq_u32_e32 vcc, 0, v2
	s_and_saveexec_b64 s[10:11], vcc
	s_cbranch_execz .LBB0_122
	s_bcnt1_i32_b64 s3, s[8:9]
	v_mov_b32_e32 v2, 0x2000
	v_mov_b32_e32 v3, s3
.LBB0_122:
	s_or_b64 exec, exec, s[10:11]
.LBB0_123:
	s_or_b64 exec, exec, s[4:5]
	s_waitcnt lgkmcnt(0)
	s_barrier

.LBB0_200:
	s_or_b64 exec, exec, s[10:11]
.LBB0_201:
	s_or_b64 exec, exec, s[4:5]
	s_waitcnt lgkmcnt(0)
	s_barrier

.LBB0_448:
	s_or_b64 exec, exec, s[6:7]
	s_mov_b64 s[6:7], exec
	v_mbcnt_lo_u32_b32 v2, s6, 0
	v_mbcnt_hi_u32_b32 v2, s7, v2
	v_cmp_eq_u32_e32 vcc, 0, v2
	s_and_saveexec_b64 s[8:9], vcc
	s_cbranch_execz .LBB0_450
	s_bcnt1_i32_b64 s3, s[6:7]
	v_mov_b32_e32 v2, 0x2000
	v_mov_b32_e32 v3, s3
.LBB0_450:
	s_or_b64 exec, exec, s[8:9]
.LBB0_451:
	s_or_b64 exec, exec, s[0:1]
	s_waitcnt lgkmcnt(0)
	s_barrier

.LBB0_619:
	s_or_b64 exec, exec, s[8:9]
	s_mov_b64 s[8:9], exec
	v_mbcnt_lo_u32_b32 v1, s8, 0
	v_mbcnt_hi_u32_b32 v1, s9, v1
	v_cmp_eq_u32_e32 vcc, 0, v1
	s_and_saveexec_b64 s[10:11], vcc
	s_cbranch_execz .LBB0_621
	s_bcnt1_i32_b64 s3, s[8:9]
	v_mov_b32_e32 v1, 0x2000
	v_mov_b32_e32 v2, s3
.LBB0_621:
	s_or_b64 exec, exec, s[10:11]
.LBB0_622:
	s_or_b64 exec, exec, s[4:5]
	s_waitcnt lgkmcnt(0)
	s_barrier

.LBB0_694:
	s_or_b64 exec, exec, s[10:11]
	s_mov_b64 s[10:11], exec
	v_mbcnt_lo_u32_b32 v1, s10, 0
	v_mbcnt_hi_u32_b32 v1, s11, v1
	v_cmp_eq_u32_e32 vcc, 0, v1
	s_and_saveexec_b64 s[12:13], vcc
	s_cbranch_execz .LBB0_696
	s_bcnt1_i32_b64 s3, s[10:11]
	v_mov_b32_e32 v1, 0x2000
	v_mov_b32_e32 v2, s3
.LBB0_696:
	s_or_b64 exec, exec, s[12:13]
.LBB0_697:
	s_or_b64 exec, exec, s[4:5]
	s_waitcnt lgkmcnt(0)
	s_barrier

.LBB0_703:
	s_abs_i32 s4, s42
	s_mul_hi_u32 s5, s4, s29
	s_mul_i32 s14, s5, s25
	s_ashr_i32 s3, s42, 31
	s_sub_i32 s4, s4, s14
	s_xor_b32 s3, s3, s28
	s_add_i32 s14, s5, 1
	s_sub_i32 s15, s4, s25
	s_cmp_ge_u32 s4, s25
	s_cselect_b32 s5, s14, s5
	s_cselect_b32 s4, s15, s4
	s_add_i32 s14, s5, 1
	s_cmp_ge_u32 s4, s25
	s_cselect_b32 s4, s14, s5
	s_xor_b32 s4, s4, s3
	s_sub_i32 s3, s4, s3
	s_mul_i32 s4, s3, s62
	s_sub_i32 s4, s42, s4
	s_and_b32 s5, s4, 7
	s_ashr_i32 s4, s4, 3
	s_mul_i32 s3, s3, s18
	s_add_i32 s3, s3, s4
	s_ashr_i32 s4, s3, 31
	s_lshr_b32 s4, s4, 27
	s_add_i32 s4, s3, s4
	s_ashr_i32 s14, s4, 5
	s_andn2_b32 s4, s4, 31
	s_sub_i32 s3, s3, s4
	s_lshl_b32 s4, s14, 3
	s_or_b32 s4, s4, s5
	s_lshr_b32 s5, s4, 31
	s_add_i32 s5, s4, s5
	s_and_b32 s14, s5, 0x3ffffffe
	s_sub_i32 s4, s4, s14
	s_bfe_u32 s14, s5, 0x10003
	s_xor_b32 s4, s4, s14
	s_ashr_i32 s14, s3, 31
	s_lshr_b32 s14, s14, 30
	s_add_i32 s14, s3, s14
	s_ashr_i32 s15, s14, 2
	s_and_b32 s14, s14, -4
	s_lshl_b32 s4, s4, 2
	s_sub_i32 s3, s3, s14
	s_add_i32 s43, s4, s3
	s_lshl_b32 s3, s5, 2
	s_and_b32 s3, s3, -8
	s_add_i32 s44, s3, s15

.LBB0_790:
	s_or_b64 exec, exec, s[12:13]
.LBB0_791:
	s_or_b64 exec, exec, s[4:5]
	s_waitcnt lgkmcnt(0)
	s_barrier

.LBB0_873:
	s_or_b64 exec, exec, s[10:11]
	s_mov_b64 s[10:11], exec
	v_mbcnt_lo_u32_b32 v0, s10, 0
	v_mbcnt_hi_u32_b32 v0, s11, v0
	v_cmp_eq_u32_e32 vcc, 0, v0
	s_and_saveexec_b64 s[12:13], vcc
	s_cbranch_execz .LBB0_875
	s_bcnt1_i32_b64 s3, s[10:11]
	v_mov_b32_e32 v0, 0x2000
	v_mov_b32_e32 v1, s3
.LBB0_875:
	s_or_b64 exec, exec, s[12:13]
.LBB0_876:
	s_or_b64 exec, exec, s[4:5]
	s_waitcnt lgkmcnt(0)
	s_barrier
